# spatial-gate epilogue: the four b_s row-bias loads issued together before the stores (was load, wait for all prior stores, 8 stores, repeated 4x)
# baseline (speedup 1.0000x reference)
; __device__ __forceinline__ int crow(int r,int hi){return (r&3)+8*(r>>2)+4*hi;}
; __device__ __forceinline__ unsigned f2bf(float f) { unsigned u = __builtin_bit_cast(unsigned, f); return (u + 0x7fffu + ((u >> 16) & 1u)) >> 16; }
; __device__ __forceinline__ int crow(int r, int hi) { return (r & 3) + 8 * (r >> 2) + 4 * hi; }
; __device__ __forceinline__ void sgate_unit(const Args& a, LAS unsigned char* lds, int c, int tid, int wave, int lane) {
;     ...
; #pragma unroll
;             for (int r = 0; r < 16; ++r) { const int i = iblk * 32 + crow(r, hi);
;                 const size_t ro = (size_t)(row0 + i); const int col = g * 128 + cpair * 64 + r32;
;                 const float bs = a.in[I_BS][g * 128 + i];
;                 CAT[ro * 2048 + col] = (bf16)f2bf(bflo(uu[r]) * (acc0[r] + bs)); CAT[ro * 2048 + col + 32] = (bf16)f2bf(bfhi(uu[r]) * (acc1[r] + bs)); }
.LBB0_337:
	v_add_u32_e32 v82, s30, v206
	v_ashrrev_i32_e32 v83, 31, v82
	v_lshl_add_u64 v[82:83], v[82:83], 2, s[56:57]
	global_load_dwordx4 v[92:95], v[82:83], off
	global_load_dwordx4 v[72:75], v[82:83], off offset:32
	global_load_dwordx4 v[76:79], v[82:83], off offset:64
	global_load_dwordx4 v[48:51], v[82:83], off offset:96
	s_waitcnt vmcnt(35)
	v_lshlrev_b32_e32 v96, 16, v221
	s_waitcnt vmcnt(34)
	v_lshlrev_b32_e32 v98, 16, v222
	v_lshl_add_u64 v[80:81], v[186:187], 1, s[46:47]
	s_waitcnt vmcnt(32)
	v_lshlrev_b32_e32 v99, 16, v223
	s_waitcnt vmcnt(30)
	v_lshlrev_b32_e32 v100, 16, v224
	s_waitcnt vmcnt(28)
	v_lshlrev_b32_e32 v101, 16, v225
	s_waitcnt vmcnt(26)
	v_lshlrev_b32_e32 v102, 16, v226
	s_waitcnt vmcnt(24)
	v_lshlrev_b32_e32 v103, 16, v227
	s_waitcnt vmcnt(22)
	v_lshlrev_b32_e32 v222, 16, v228
	s_waitcnt vmcnt(20)
	v_lshlrev_b32_e32 v223, 16, v229
	s_waitcnt vmcnt(18)
	v_lshlrev_b32_e32 v91, 16, v230
	s_waitcnt vmcnt(16)
	v_lshlrev_b32_e32 v90, 16, v231
	s_waitcnt vmcnt(14)
	v_lshlrev_b32_e32 v89, 16, v232
	s_waitcnt vmcnt(12)
	v_lshlrev_b32_e32 v88, 16, v233
	s_waitcnt vmcnt(10)
	v_lshlrev_b32_e32 v87, 16, v234
	s_waitcnt vmcnt(8)
	v_lshlrev_b32_e32 v86, 16, v235
	s_waitcnt vmcnt(6)
	v_lshlrev_b32_e32 v85, 16, v236
	s_waitcnt vmcnt(4)
	v_lshlrev_b32_e32 v84, 16, v237
	s_mov_b32 s4, 8
	s_andn2_b64 vcc, exec, s[6:7]
	s_waitcnt vmcnt(0)
	v_add_f32_e32 v16, v16, v92
	v_mul_f32_e32 v16, v16, v96
	v_bfe_u32 v96, v16, 16, 1
	v_add_f32_e32 v0, v0, v92
	v_add3_u32 v16, v16, v96, s84
	v_lshl_add_u64 v[96:97], v[80:81], 0, v[150:151]
	v_mul_f32_e32 v0, v0, v98
	global_store_short_d16_hi v[96:97], v16, off
	v_bfe_u32 v16, v0, 16, 1
	v_add3_u32 v0, v0, v16, s84
	global_store_short_d16_hi v[96:97], v0, off offset:64
	v_lshlrev_b32_e32 v0, 16, v220
	v_add_f32_e32 v16, v17, v93
	v_mul_f32_e32 v0, v16, v0
	v_bfe_u32 v16, v0, 16, 1
	v_add3_u32 v0, v0, v16, s84
	v_lshl_add_u64 v[16:17], v[80:81], 0, v[152:153]
	global_store_short_d16_hi v[16:17], v0, off
	v_add_f32_e32 v0, v1, v93
	v_mul_f32_e32 v0, v0, v99
	v_bfe_u32 v1, v0, 16, 1
	v_add3_u32 v0, v0, v1, s84
	global_store_short_d16_hi v[16:17], v0, off offset:64
	v_lshlrev_b32_e32 v0, 16, v219
	v_add_f32_e32 v1, v18, v94
	v_mul_f32_e32 v0, v1, v0
	v_bfe_u32 v1, v0, 16, 1
	v_add_f32_e32 v2, v2, v94
	v_add3_u32 v16, v0, v1, s84
	v_lshl_add_u64 v[0:1], v[80:81], 0, v[154:155]
	v_mul_f32_e32 v2, v2, v100
	global_store_short_d16_hi v[0:1], v16, off
	v_bfe_u32 v16, v2, 16, 1
	v_add3_u32 v2, v2, v16, s84
	global_store_short_d16_hi v[0:1], v2, off offset:64
	v_lshlrev_b32_e32 v0, 16, v218
	v_add_f32_e32 v1, v19, v95
	v_mul_f32_e32 v0, v1, v0
	v_bfe_u32 v1, v0, 16, 1
	v_add3_u32 v2, v0, v1, s84
	v_lshl_add_u64 v[0:1], v[80:81], 0, v[156:157]
	global_store_short_d16_hi v[0:1], v2, off
	v_add_f32_e32 v2, v3, v95
	v_mul_f32_e32 v2, v2, v101
	v_bfe_u32 v3, v2, 16, 1
	v_add3_u32 v2, v2, v3, s84
	global_store_short_d16_hi v[0:1], v2, off offset:64
	v_mov_b32_e32 v0, v72
	v_mov_b32_e32 v1, v73
	v_mov_b32_e32 v2, v74
	v_mov_b32_e32 v3, v75
	v_lshlrev_b32_e32 v16, 16, v217
	s_nop 0
	v_add_f32_e32 v17, v20, v0
	v_add_f32_e32 v0, v4, v0
	v_mul_f32_e32 v16, v17, v16
	v_mul_f32_e32 v0, v0, v102
	v_bfe_u32 v17, v16, 16, 1
	v_bfe_u32 v4, v0, 16, 1
	v_add3_u32 v18, v16, v17, s84
	v_lshl_add_u64 v[16:17], v[80:81], 0, v[158:159]
	v_add3_u32 v0, v0, v4, s84
	global_store_short_d16_hi v[16:17], v0, off offset:64
	v_lshlrev_b32_e32 v0, 16, v216
	v_add_f32_e32 v4, v21, v1
	v_mul_f32_e32 v0, v4, v0
	v_bfe_u32 v4, v0, 16, 1
	global_store_short_d16_hi v[16:17], v18, off
	v_add3_u32 v0, v0, v4, s84
	v_lshl_add_u64 v[16:17], v[80:81], 0, v[160:161]
	global_store_short_d16_hi v[16:17], v0, off
	v_add_f32_e32 v0, v5, v1
	v_mul_f32_e32 v0, v0, v103
	v_bfe_u32 v1, v0, 16, 1
	v_add3_u32 v0, v0, v1, s84
	global_store_short_d16_hi v[16:17], v0, off offset:64
	v_lshlrev_b32_e32 v0, 16, v215
	v_add_f32_e32 v1, v22, v2
	v_mul_f32_e32 v0, v1, v0
	v_bfe_u32 v1, v0, 16, 1
	v_add_f32_e32 v2, v6, v2
	v_add3_u32 v4, v0, v1, s84
	v_lshl_add_u64 v[0:1], v[80:81], 0, v[162:163]
	v_mul_f32_e32 v2, v2, v222
	global_store_short_d16_hi v[0:1], v4, off
	v_bfe_u32 v4, v2, 16, 1
	v_add3_u32 v2, v2, v4, s84
	global_store_short_d16_hi v[0:1], v2, off offset:64
	v_lshlrev_b32_e32 v0, 16, v214
	v_add_f32_e32 v1, v23, v3
	v_mul_f32_e32 v0, v1, v0
	v_bfe_u32 v1, v0, 16, 1
	v_add3_u32 v2, v0, v1, s84
	v_lshl_add_u64 v[0:1], v[80:81], 0, v[164:165]
	global_store_short_d16_hi v[0:1], v2, off
	v_add_f32_e32 v2, v7, v3
	v_mul_f32_e32 v2, v2, v223
	v_bfe_u32 v3, v2, 16, 1
	v_add3_u32 v2, v2, v3, s84
	global_store_short_d16_hi v[0:1], v2, off offset:64
	v_mov_b32_e32 v0, v76
	v_mov_b32_e32 v1, v77
	v_mov_b32_e32 v2, v78
	v_mov_b32_e32 v3, v79
	v_lshlrev_b32_e32 v4, 16, v213
	s_nop 0
	v_add_f32_e32 v5, v24, v0
	v_mul_f32_e32 v4, v5, v4
	v_bfe_u32 v5, v4, 16, 1
	v_add_f32_e32 v0, v8, v0
	v_add3_u32 v6, v4, v5, s84
	v_lshl_add_u64 v[4:5], v[80:81], 0, v[166:167]
	v_mul_f32_e32 v0, v0, v91
	global_store_short_d16_hi v[4:5], v6, off
	v_bfe_u32 v6, v0, 16, 1
	v_add3_u32 v0, v0, v6, s84
	global_store_short_d16_hi v[4:5], v0, off offset:64
	v_lshlrev_b32_e32 v0, 16, v212
	v_add_f32_e32 v4, v25, v1
	v_mul_f32_e32 v0, v4, v0
	v_bfe_u32 v4, v0, 16, 1
	v_add3_u32 v0, v0, v4, s84
	v_lshl_add_u64 v[4:5], v[80:81], 0, v[168:169]
	global_store_short_d16_hi v[4:5], v0, off
	v_add_f32_e32 v0, v9, v1
	v_mul_f32_e32 v0, v0, v90
	v_bfe_u32 v1, v0, 16, 1
	v_add3_u32 v0, v0, v1, s84
	global_store_short_d16_hi v[4:5], v0, off offset:64
	v_lshlrev_b32_e32 v0, 16, v211
	v_add_f32_e32 v1, v26, v2
	v_mul_f32_e32 v0, v1, v0
	v_bfe_u32 v1, v0, 16, 1
	v_add_f32_e32 v2, v10, v2
; __device__ __forceinline__ int crow(int r,int hi){return (r&3)+8*(r>>2)+4*hi;}
; __device__ __forceinline__ unsigned f2bf(float f) { unsigned u = __builtin_bit_cast(unsigned, f); return (u + 0x7fffu + ((u >> 16) & 1u)) >> 16; }
; __device__ __forceinline__ int crow(int r, int hi) { return (r & 3) + 8 * (r >> 2) + 4 * hi; }
; __device__ __forceinline__ void sgate_unit(const Args& a, LAS unsigned char* lds, int c, int tid, int wave, int lane) {
;     ...
; #pragma unroll
;             for (int r = 0; r < 16; ++r) { const int i = iblk * 32 + crow(r, hi);
;                 const size_t ro = (size_t)(row0 + i); const int col = g * 128 + cpair * 64 + r32;
;                 const float bs = a.in[I_BS][g * 128 + i];
;                 CAT[ro * 2048 + col] = (bf16)f2bf(bflo(uu[r]) * (acc0[r] + bs)); CAT[ro * 2048 + col + 32] = (bf16)f2bf(bfhi(uu[r]) * (acc1[r] + bs)); }
	v_add3_u32 v4, v0, v1, s84
	v_lshl_add_u64 v[0:1], v[80:81], 0, v[170:171]
	v_mul_f32_e32 v2, v2, v89
	global_store_short_d16_hi v[0:1], v4, off
	v_bfe_u32 v4, v2, 16, 1
	v_add3_u32 v2, v2, v4, s84
	global_store_short_d16_hi v[0:1], v2, off offset:64
	v_lshlrev_b32_e32 v0, 16, v210
	v_add_f32_e32 v1, v27, v3
	v_mul_f32_e32 v0, v1, v0
	v_bfe_u32 v1, v0, 16, 1
	v_add3_u32 v2, v0, v1, s84
	v_lshl_add_u64 v[0:1], v[80:81], 0, v[172:173]
	global_store_short_d16_hi v[0:1], v2, off
	v_add_f32_e32 v2, v11, v3
	v_mul_f32_e32 v2, v2, v88
	v_bfe_u32 v3, v2, 16, 1
	v_add3_u32 v2, v2, v3, s84
	global_store_short_d16_hi v[0:1], v2, off offset:64
	v_mov_b32_e32 v0, v48
	v_mov_b32_e32 v1, v49
	v_mov_b32_e32 v2, v50
	v_mov_b32_e32 v3, v51
	v_lshlrev_b32_e32 v4, 16, v209
	s_nop 0
	v_add_f32_e32 v5, v28, v0
	v_mul_f32_e32 v4, v5, v4
	v_bfe_u32 v5, v4, 16, 1
	v_add_f32_e32 v0, v12, v0
	v_add3_u32 v6, v4, v5, s84
	v_lshl_add_u64 v[4:5], v[80:81], 0, v[174:175]
	v_mul_f32_e32 v0, v0, v87
	global_store_short_d16_hi v[4:5], v6, off
	v_bfe_u32 v6, v0, 16, 1
	v_add3_u32 v0, v0, v6, s84
	global_store_short_d16_hi v[4:5], v0, off offset:64
	v_lshlrev_b32_e32 v0, 16, v208
	v_add_f32_e32 v4, v29, v1
	v_mul_f32_e32 v0, v4, v0
	v_bfe_u32 v4, v0, 16, 1
	v_add3_u32 v0, v0, v4, s84
	v_lshl_add_u64 v[4:5], v[80:81], 0, v[176:177]
	global_store_short_d16_hi v[4:5], v0, off
	v_add_f32_e32 v0, v13, v1
	v_mul_f32_e32 v0, v0, v86
	v_bfe_u32 v1, v0, 16, 1
	v_add3_u32 v0, v0, v1, s84
	global_store_short_d16_hi v[4:5], v0, off offset:64
	v_lshlrev_b32_e32 v0, 16, v185
	v_add_f32_e32 v1, v30, v2
	v_mul_f32_e32 v0, v1, v0
	v_bfe_u32 v1, v0, 16, 1
	v_add_f32_e32 v2, v14, v2
	v_add3_u32 v4, v0, v1, s84
	v_lshl_add_u64 v[0:1], v[80:81], 0, v[178:179]
	v_mul_f32_e32 v2, v2, v85
	global_store_short_d16_hi v[0:1], v4, off
	v_bfe_u32 v4, v2, 16, 1
	v_add3_u32 v2, v2, v4, s84
	global_store_short_d16_hi v[0:1], v2, off offset:64
	v_lshlrev_b32_e32 v0, 16, v112
	v_add_f32_e32 v1, v31, v3
	v_mul_f32_e32 v0, v1, v0
	v_bfe_u32 v1, v0, 16, 1
	v_add3_u32 v2, v0, v1, s84
	v_lshl_add_u64 v[0:1], v[80:81], 0, v[180:181]
	global_store_short_d16_hi v[0:1], v2, off
	v_add_f32_e32 v2, v15, v3
	v_mul_f32_e32 v2, v2, v84
	v_bfe_u32 v3, v2, 16, 1
	v_add3_u32 v2, v2, v3, s84
	global_store_short_d16_hi v[0:1], v2, off offset:64
	s_cbranch_vccnz .LBB0_324
	s_add_i32 s4, s20, 1
	s_lshl_b32 s20, s4, 7
	s_lshl_b64 s[6:7], s[20:21], 2
	v_lshl_add_u64 v[12:13], v[114:115], 0, s[6:7]
	ds_read_b64 v[8:9], v197
	v_lshl_add_u64 v[10:11], v[116:117], 0, s[6:7]
	global_load_dwordx4 v[0:3], v[12:13], off
	global_load_dwordx4 v[4:7], v[10:11], off
	v_lshlrev_b32_e32 v14, 16, v33
	v_and_b32_e32 v15, 0xffff0000, v33
	s_waitcnt lgkmcnt(0)
	v_sub_f32_e32 v15, v15, v8
	v_sub_f32_e32 v14, v14, v8
	v_lshlrev_b32_e32 v16, 16, v32
	v_and_b32_e32 v17, 0xffff0000, v32
	v_lshlrev_b32_e32 v19, 16, v34
	v_and_b32_e32 v20, 0xffff0000, v34
	v_lshlrev_b32_e32 v21, 16, v35
	v_and_b32_e32 v24, 0xffff0000, v35
	v_pk_mul_f32 v[14:15], v[8:9], v[14:15] op_sel:[1,0]
	v_sub_f32_e32 v17, v17, v8
	v_sub_f32_e32 v16, v16, v8
	v_pk_mul_f32 v[16:17], v[8:9], v[16:17] op_sel:[1,0]
	s_lshl_b32 s5, s4, 15
	s_and_b32 s5, s5, 0x8000
	v_add_u32_e32 v18, s5, v196
	v_lshlrev_b32_e32 v28, 16, v39
	v_and_b32_e32 v29, 0xffff0000, v39
	s_waitcnt vmcnt(0)
	v_pk_fma_f32 v[22:23], v[2:3], v[14:15], v[6:7]
	v_sub_f32_e32 v15, v24, v8
	v_sub_f32_e32 v14, v21, v8
	v_sub_f32_e32 v21, v20, v8
	v_sub_f32_e32 v20, v19, v8
	v_pk_mul_f32 v[20:21], v[8:9], v[20:21] op_sel:[1,0]
	v_pk_mul_f32 v[24:25], v[8:9], v[14:15] op_sel:[1,0]
	global_load_dwordx4 v[8:11], v[10:11], off offset:16
	s_nop 0
	global_load_dwordx4 v[12:15], v[12:13], off offset:16
	v_pk_fma_f32 v[16:17], v[0:1], v[16:17], v[4:5]
	v_lshlrev_b32_e32 v19, 16, v36
	s_waitcnt vmcnt(0)
	v_pk_fma_f32 v[24:25], v[14:15], v[24:25], v[10:11]
	v_pk_fma_f32 v[26:27], v[12:13], v[20:21], v[8:9]
	v_cvt_pk_bf16_f32 v20, v16, v17
	v_cvt_pk_bf16_f32 v21, v22, v23
	v_cvt_pk_bf16_f32 v22, v26, v27
	v_cvt_pk_bf16_f32 v23, v24, v25
	v_add_u32_e32 v16, v18, v195
	ds_write_b128 v16, v[20:23]
	ds_read_b64 v[16:17], v198
	v_and_b32_e32 v22, 0xffff0000, v36
	v_lshlrev_b32_e32 v20, 16, v37
	v_and_b32_e32 v21, 0xffff0000, v37
	v_lshlrev_b32_e32 v26, 16, v38
	s_waitcnt lgkmcnt(0)
	v_sub_f32_e32 v21, v21, v16
	v_sub_f32_e32 v20, v20, v16
	v_sub_f32_e32 v23, v22, v16
	v_sub_f32_e32 v22, v19, v16
	v_and_b32_e32 v27, 0xffff0000, v38
	v_pk_mul_f32 v[22:23], v[16:17], v[22:23] op_sel:[1,0]
	v_pk_mul_f32 v[20:21], v[16:17], v[20:21] op_sel:[1,0]
	v_sub_f32_e32 v27, v27, v16
	v_pk_fma_f32 v[24:25], v[2:3], v[20:21], v[6:7]
	v_pk_fma_f32 v[20:21], v[0:1], v[22:23], v[4:5]
	v_sub_f32_e32 v23, v29, v16
	v_sub_f32_e32 v22, v28, v16
	v_sub_f32_e32 v26, v26, v16
	v_pk_mul_f32 v[26:27], v[16:17], v[26:27] op_sel:[1,0]
	v_pk_mul_f32 v[16:17], v[16:17], v[22:23] op_sel:[1,0]
	v_pk_fma_f32 v[22:23], v[12:13], v[26:27], v[8:9]
	v_pk_fma_f32 v[16:17], v[14:15], v[16:17], v[10:11]
	v_cvt_pk_bf16_f32 v20, v20, v21
	v_cvt_pk_bf16_f32 v21, v24, v25
	v_cvt_pk_bf16_f32 v22, v22, v23
	v_cvt_pk_bf16_f32 v23, v16, v17
	v_add_u32_e32 v16, v18, v199
	ds_write_b128 v16, v[20:23]
	ds_read_b64 v[16:17], v200
	v_lshlrev_b32_e32 v19, 16, v40
	v_and_b32_e32 v22, 0xffff0000, v40
	v_lshlrev_b32_e32 v20, 16, v41
	v_and_b32_e32 v21, 0xffff0000, v41
	s_waitcnt lgkmcnt(0)
	v_sub_f32_e32 v21, v21, v16
	v_sub_f32_e32 v20, v20, v16
	v_sub_f32_e32 v23, v22, v16
	v_sub_f32_e32 v22, v19, v16
	v_lshlrev_b32_e32 v26, 16, v42
	v_and_b32_e32 v27, 0xffff0000, v42
	v_lshlrev_b32_e32 v28, 16, v43
	v_and_b32_e32 v29, 0xffff0000, v43
	v_pk_mul_f32 v[22:23], v[16:17], v[22:23] op_sel:[1,0]
	v_pk_mul_f32 v[20:21], v[16:17], v[20:21] op_sel:[1,0]
	v_sub_f32_e32 v27, v27, v16
	v_pk_fma_f32 v[24:25], v[2:3], v[20:21], v[6:7]
	v_pk_fma_f32 v[20:21], v[0:1], v[22:23], v[4:5]
	v_sub_f32_e32 v23, v29, v16
	v_sub_f32_e32 v22, v28, v16
	v_sub_f32_e32 v26, v26, v16
	v_pk_mul_f32 v[26:27], v[16:17], v[26:27] op_sel:[1,0]
	v_pk_mul_f32 v[16:17], v[16:17], v[22:23] op_sel:[1,0]
	v_pk_fma_f32 v[22:23], v[12:13], v[26:27], v[8:9]
	v_pk_fma_f32 v[16:17], v[14:15], v[16:17], v[10:11]
	v_cvt_pk_bf16_f32 v20, v20, v21
	v_cvt_pk_bf16_f32 v21, v24, v25
	v_cvt_pk_bf16_f32 v22, v22, v23
	v_cvt_pk_bf16_f32 v23, v16, v17
	v_add_u32_e32 v16, v18, v201
	ds_write_b128 v16, v[20:23]
	ds_read_b64 v[16:17], v202
	v_lshlrev_b32_e32 v19, 16, v44
	v_and_b32_e32 v22, 0xffff0000, v44
	v_lshlrev_b32_e32 v20, 16, v45
	v_and_b32_e32 v21, 0xffff0000, v45
	s_waitcnt lgkmcnt(0)
	v_sub_f32_e32 v21, v21, v16
	v_sub_f32_e32 v20, v20, v16
	v_sub_f32_e32 v23, v22, v16
	v_sub_f32_e32 v22, v19, v16
	v_lshlrev_b32_e32 v24, 16, v46
	v_and_b32_e32 v25, 0xffff0000, v46
	v_lshlrev_b32_e32 v26, 16, v47
	v_and_b32_e32 v27, 0xffff0000, v47
	v_pk_mul_f32 v[22:23], v[16:17], v[22:23] op_sel:[1,0]
	v_pk_mul_f32 v[20:21], v[16:17], v[20:21] op_sel:[1,0]
	v_pk_fma_f32 v[0:1], v[0:1], v[22:23], v[4:5]
	v_pk_fma_f32 v[2:3], v[2:3], v[20:21], v[6:7]
	v_sub_f32_e32 v5, v27, v16
	v_sub_f32_e32 v4, v26, v16
	v_sub_f32_e32 v7, v25, v16
	v_sub_f32_e32 v6, v24, v16
	v_pk_mul_f32 v[6:7], v[16:17], v[6:7] op_sel:[1,0]
	v_pk_mul_f32 v[4:5], v[16:17], v[4:5] op_sel:[1,0]
	v_pk_fma_f32 v[6:7], v[12:13], v[6:7], v[8:9]
	v_pk_fma_f32 v[4:5], v[14:15], v[4:5], v[10:11]
	v_cvt_pk_bf16_f32 v0, v0, v1
	v_cvt_pk_bf16_f32 v1, v2, v3
	v_cvt_pk_bf16_f32 v2, v6, v7
	v_cvt_pk_bf16_f32 v3, v4, v5
	v_add_u32_e32 v4, v18, v203
	ds_write_b128 v4, v[0:3]
	s_branch .LBB0_324
